# MFMA-VALU interleave: tile A row-max partial (16 v_max3) computed in tile B QK MFMA shadow for BR2/BR3 NT=2 (on top of permlane merge)
# baseline (speedup 1.0000x reference)
; #define LAS __attribute__((address_space(3)))
; DI unsigned f2bf(float f) { return pk2(f, 0.f) & 0xffffu; }
; #define MFMA32(a, b, c) __builtin_amdgcn_mfma_f32_32x32x16_bf16((a), (b), (c), 0, 0, 0)
; template <int BR, int NT, int DV> ...
;     ...
;     for (int ti = 0; ti < NT; ++ti) {
;         LAS unsigned char* kb = ti ? kbB : kbA; const int j = ti ? jB : jA;
; #pragma unroll
;         for (int i = 0; i < 16; ++i) { s[2 * ti][i] = 0.f; s[2 * ti + 1][i] = 0.f; }
; #pragma unroll
;         for (int ks = 0; ks < ((DV & 4) ? 0 : 4); ++ks) {
;             const bf16x8 a0 = *(const LAS bf16x8*)(kb + c.n * 144 + ks * 32 + c.h * 16);
;             const bf16x8 a1 = *(const LAS bf16x8*)(kb + (32 + c.n) * 144 + ks * 32 + c.h * 16);
;             s[2 * ti] = MFMA32(a0, c.qf[ks], s[2 * ti]); s[2 * ti + 1] = MFMA32(a1, c.qf[ks], s[2 * ti + 1]);
;         }
;         {
;             const int pos0 = (BR <= 1) ? (1024 * j + 31 - c.t) : (64 * j - c.t);
;             float tb = c.slope2 * (float)pos0;
;             if (BR == 2) { if (!m128_bit(c.sel_lo, c.sel_hi, j)) tb = -1e30f; }
;             const unsigned thi = f2bf(tb); const unsigned tlo = f2bf(tb - bf2f(thi));
;             u32x4 bw = (u32x4){(BR <= 1) ? c.slope16w : c.slopew, thi | (tlo << 16), 0u, 0u};
;             if (c.h) bw = (u32x4){0u, 0u, 0u, 0u};
;             const bf16x8 bb = __builtin_bit_cast(bf16x8, bw);
;             s[2 * ti] = MFMA32(c.akey[0], bb, s[2 * ti]); s[2 * ti + 1] = MFMA32(c.akey[1], bb, s[2 * ti + 1]);
;         }
;     ...
;     float mx = -INFINITY;
; #pragma unroll
;     for (int q = 0; q < 2 * NT; ++q)
; #pragma unroll
;         for (int i = 0; i < 16; ++i) mx = fmaxf(mx, s[q][i]);
.LBB0_1021:
	ds_read_b128 v[6:9], v4 offset:13888
	ds_read_b128 v[10:13], v4 offset:9312
	ds_read_b128 v[172:175], v4 offset:13920
	s_lshl_b32 s8, s20, 6
	v_sub_u32_e32 v1, s8, v209
	s_waitcnt lgkmcnt(7)
	v_mfma_f32_32x32x16_bf16 v[80:95], v[232:235], v[112:115], 0
	s_cmp_lt_i32 s20, 64
	v_cvt_f32_i32_e32 v1, v1
	s_cselect_b64 vcc, -1, 0
	s_sub_i32 s9, s20, 64
	s_cmp_lg_u32 s20, s93
	v_mul_f32_e32 v1, v210, v1
	s_waitcnt lgkmcnt(6)
	v_mfma_f32_32x32x16_bf16 v[96:111], v[236:239], v[112:115], 0
	v_max3_f32 v252, v64, s43, v65
	v_max3_f32 v252, v252, v66, v67
	s_waitcnt lgkmcnt(5)
	v_mfma_f32_32x32x16_bf16 v[96:111], v[240:243], v[116:119], v[96:111]
	v_max3_f32 v252, v252, v68, v69
	v_max3_f32 v252, v252, v70, v71
	s_waitcnt lgkmcnt(4)
	v_mfma_f32_32x32x16_bf16 v[80:95], v[244:247], v[116:119], v[80:95]
	v_max3_f32 v252, v252, v72, v73
	v_max3_f32 v252, v252, v74, v75
	s_waitcnt lgkmcnt(3)
	v_mfma_f32_32x32x16_bf16 v[96:111], v[248:251], v[120:123], v[96:111]
	v_max3_f32 v252, v252, v76, v77
	v_max3_f32 v252, v252, v78, v79
	s_waitcnt lgkmcnt(2)
	v_mfma_f32_32x32x16_bf16 v[80:95], v[6:9], v[120:123], v[80:95]
	v_max3_f32 v252, v252, v48, v49
	v_max3_f32 v252, v252, v50, v51
	v_lshrrev_b64 v[4:5], s20, v[142:143]
	s_waitcnt lgkmcnt(1)
	v_mfma_f32_32x32x16_bf16 v[96:111], v[10:13], v[124:127], v[96:111]
	v_max3_f32 v252, v252, v52, v53
	v_max3_f32 v252, v252, v54, v55
	v_lshrrev_b64 v[6:7], s9, v[144:145]
	v_cndmask_b32_e32 v3, v6, v4, vcc
	v_and_b32_e32 v3, 1, v3
	v_cmp_eq_u32_e32 vcc, 1, v3
	s_nop 1
	v_cndmask_b32_e32 v1, v207, v1, vcc
	s_waitcnt lgkmcnt(0)
	v_mfma_f32_32x32x16_bf16 v[80:95], v[172:175], v[124:127], v[80:95]
	v_max3_f32 v252, v252, v56, v57
	v_max3_f32 v252, v252, v58, v59
	v_cvt_pk_bf16_f32 v3, v1, 0
	v_and_b32_e32 v4, 0xffff, v3
	v_lshlrev_b32_e32 v3, 16, v3
	v_sub_f32_e32 v1, v1, v3
	v_cvt_pk_bf16_f32 v1, v1, 0
	v_lshl_or_b32 v1, v1, 16, v4
	v_cndmask_b32_e64 v1, 0, v1, s[6:7]
	v_mov_b32_e32 v3, v2
	s_nop 1
	v_mfma_f32_32x32x16_bf16 v[96:111], v[128:131], v[0:3], v[96:111]
	v_max3_f32 v252, v252, v60, v61
	v_max3_f32 v252, v252, v62, v63
	v_mfma_f32_32x32x16_bf16 v[80:95], v[132:135], v[0:3], v[80:95]
	s_cbranch_scc1 .LBB0_1023
	v_or_b32_e32 v0, s8, v218
	v_sub_u32_e32 v1, v209, v0
	v_cmp_lt_i32_e32 vcc, -1, v1
	v_sub_u32_e32 v1, v0, v209
	s_nop 5
	v_cndmask_b32_e32 v96, v203, v96, vcc
	v_cmp_gt_i32_e32 vcc, 0, v1
	v_sub_u32_e32 v1, v219, v0
	s_nop 0
	v_cndmask_b32_e32 v97, v203, v97, vcc
	v_cmp_lt_i32_e32 vcc, -1, v1
	v_sub_u32_e32 v1, v220, v0
	s_nop 0
	v_cndmask_b32_e32 v98, v203, v98, vcc
	v_cmp_lt_i32_e32 vcc, -1, v1
	v_or_b32_e32 v1, s8, v221
	v_sub_u32_e32 v3, v209, v1
	v_cndmask_b32_e32 v99, v203, v99, vcc
	v_cmp_lt_i32_e32 vcc, -1, v3
	v_sub_u32_e32 v3, v1, v209
	s_nop 0
	v_cndmask_b32_e32 v100, v203, v100, vcc
	v_cmp_gt_i32_e32 vcc, 0, v3
	v_sub_u32_e32 v3, v219, v1
	s_nop 0
	v_cndmask_b32_e32 v101, v203, v101, vcc
	v_cmp_lt_i32_e32 vcc, -1, v3
	v_sub_u32_e32 v3, v220, v1
	s_nop 0
	v_cndmask_b32_e32 v102, v203, v102, vcc
	v_cmp_lt_i32_e32 vcc, -1, v3
	v_or_b32_e32 v3, s8, v222
	v_sub_u32_e32 v4, v209, v3
	v_cndmask_b32_e32 v103, v203, v103, vcc
	v_cmp_lt_i32_e32 vcc, -1, v4
	v_sub_u32_e32 v4, v3, v209
	s_nop 0
	v_cndmask_b32_e32 v104, v203, v104, vcc
	v_cmp_gt_i32_e32 vcc, 0, v4
	v_sub_u32_e32 v4, v219, v3
	s_nop 0
	v_cndmask_b32_e32 v105, v203, v105, vcc
	v_cmp_lt_i32_e32 vcc, -1, v4
	v_sub_u32_e32 v4, v220, v3
	s_nop 0
	v_cndmask_b32_e32 v106, v203, v106, vcc
	v_cmp_lt_i32_e32 vcc, -1, v4
	v_or_b32_e32 v4, s8, v223
	v_sub_u32_e32 v5, v209, v4
	v_cndmask_b32_e32 v107, v203, v107, vcc
	v_cmp_lt_i32_e32 vcc, -1, v5
	v_sub_u32_e32 v5, v4, v209
	s_nop 0
	v_cndmask_b32_e32 v108, v203, v108, vcc
	v_cmp_gt_i32_e32 vcc, 0, v5
	v_sub_u32_e32 v5, v219, v4
	s_nop 0
	v_cndmask_b32_e32 v109, v203, v109, vcc
	v_cmp_lt_i32_e32 vcc, -1, v5
	v_sub_u32_e32 v5, v220, v4
	s_nop 0
	v_cndmask_b32_e32 v110, v203, v110, vcc
	v_cmp_lt_i32_e32 vcc, -1, v5
	v_sub_u32_e32 v5, v224, v0
	s_nop 0
	v_cndmask_b32_e32 v111, v203, v111, vcc
	v_cmp_lt_i32_e32 vcc, -1, v5
	v_sub_u32_e32 v5, v225, v0
	s_nop 0
	v_cndmask_b32_e32 v80, v203, v80, vcc
	v_cmp_lt_i32_e32 vcc, -1, v5
	v_sub_u32_e32 v5, v226, v0
	v_sub_u32_e32 v0, v227, v0
	v_cndmask_b32_e32 v81, v203, v81, vcc
	v_cmp_lt_i32_e32 vcc, -1, v5
	s_nop 1
	v_cndmask_b32_e32 v82, v203, v82, vcc
	v_cmp_lt_i32_e32 vcc, -1, v0
	v_sub_u32_e32 v0, v224, v1
	s_nop 0
	v_cndmask_b32_e32 v83, v203, v83, vcc
	v_cmp_lt_i32_e32 vcc, -1, v0
	v_sub_u32_e32 v0, v225, v1
	s_nop 0
	v_cndmask_b32_e32 v84, v203, v84, vcc
	v_cmp_lt_i32_e32 vcc, -1, v0
	v_sub_u32_e32 v0, v226, v1
	s_nop 0
	v_cndmask_b32_e32 v85, v203, v85, vcc
	v_cmp_lt_i32_e32 vcc, -1, v0
	v_sub_u32_e32 v0, v227, v1
	s_nop 0
	v_cndmask_b32_e32 v86, v203, v86, vcc
	v_cmp_lt_i32_e32 vcc, -1, v0
	v_sub_u32_e32 v0, v224, v3
	s_nop 0
	v_cndmask_b32_e32 v87, v203, v87, vcc
	v_cmp_lt_i32_e32 vcc, -1, v0
	v_sub_u32_e32 v0, v225, v3
	s_nop 0
	v_cndmask_b32_e32 v88, v203, v88, vcc
	v_cmp_lt_i32_e32 vcc, -1, v0
	v_sub_u32_e32 v0, v226, v3
	s_nop 0
	v_cndmask_b32_e32 v89, v203, v89, vcc
	v_cmp_lt_i32_e32 vcc, -1, v0
	v_sub_u32_e32 v0, v227, v3
	s_nop 0
	v_cndmask_b32_e32 v90, v203, v90, vcc
	v_cmp_lt_i32_e32 vcc, -1, v0
	v_sub_u32_e32 v0, v224, v4
	s_nop 0
	v_cndmask_b32_e32 v91, v203, v91, vcc
	v_cmp_lt_i32_e32 vcc, -1, v0
	v_sub_u32_e32 v0, v225, v4
	s_nop 0
	v_cndmask_b32_e32 v92, v203, v92, vcc
	v_cmp_lt_i32_e32 vcc, -1, v0
	v_sub_u32_e32 v0, v226, v4
	s_nop 0
	v_cndmask_b32_e32 v93, v203, v93, vcc
	v_cmp_lt_i32_e32 vcc, -1, v0
	v_sub_u32_e32 v0, v227, v4
	s_nop 0
	v_cndmask_b32_e32 v94, v203, v94, vcc
	v_cmp_lt_i32_e32 vcc, -1, v0
	s_nop 1
	v_cndmask_b32_e32 v95, v203, v95, vcc
; template <int BR, int NT, int DV> ...
;     ...
;     float mx = -INFINITY;
; #pragma unroll
;     for (int q = 0; q < 2 * NT; ++q)
; #pragma unroll
;         for (int i = 0; i < 16; ++i) mx = fmaxf(mx, s[q][i]);
;     if (BR == 1) { m_use = m_fin; }
;     else {
;         mx = fmaxf(mx, __shfl_xor(mx, 32));
;         if (mx < -1e29f) mx = -INFINITY;
;         const float m_new = fmaxf(m, mx);
;         grow = m_new > m;
;         m_use = (m_new == -INFINITY) ? 0.f : m_new;
;         alpha = __builtin_amdgcn_exp2f(m - m_use);
;         m = m_new;
;     }
;     if (__builtin_amdgcn_ballot_w64((mx - m_use) > -150.f) == 0ull) {
;         if (BR == 1) {
; #pragma unroll
;             for (int ti = 0; ti < NT; ++ti)
; #pragma unroll
;                 for (int kt = 0; kt < 2; ++kt)
; #pragma unroll
;                     for (int v = 0; v < 4; ++v) { const int j = ti ? jB : jA; const float add = c.h ? 0.f : carry; carry = 0.f; if (c.r == 0) imp_row[16 * j + 8 * kt + 2 * v + c.h] = add; }
;         }
;         return;
;     }
;     f32x2_t sum2 = {0.f, 0.f}; const f32x2_t mm2 = {m_use, m_use}, il2 = {inv_l, inv_l};
; #pragma unroll
;     for (int q = 0; q < 2 * NT; ++q)
; #pragma unroll
;         for (int rr = 0; rr < 16; rr += 2) {
;             const f32x2_t d = (f32x2_t){s[q][rr], s[q][rr + 1]} - mm2;
;             f32x2_t p = (DV & 1) ? d : (f32x2_t){__builtin_amdgcn_exp2f(d.x), __builtin_amdgcn_exp2f(d.y)};
;             if (BR == 1) p *= il2;
;             s[q][rr] = p.x; s[q][rr + 1] = p.y; sum2 += p;
;         }
;     float sum = sum2.x + sum2.y;
;     if (BR != 1) { sum += __shfl_xor(sum, 32); l = l * alpha + sum; }
.LBB0_1023:
	v_max3_f32 v0, v252, v96, v97
	v_max3_f32 v0, v0, v98, v99
	v_max3_f32 v0, v0, v100, v101
	v_max3_f32 v0, v0, v102, v103
	v_max3_f32 v0, v0, v104, v105
	v_max3_f32 v0, v0, v106, v107
	v_max3_f32 v0, v0, v108, v109
	v_max3_f32 v0, v0, v110, v111
	v_max3_f32 v0, v0, v80, v81
	v_max3_f32 v0, v0, v82, v83
	v_max3_f32 v0, v0, v84, v85
	v_max3_f32 v0, v0, v86, v87
	v_max3_f32 v0, v0, v88, v89
	v_max3_f32 v0, v0, v90, v91
	v_max3_f32 v0, v0, v92, v93
	v_max3_f32 v0, v0, v94, v95
	ds_bpermute_b32 v1, v215, v0
	v_max_f32_e32 v3, v230, v230
	s_waitcnt lgkmcnt(0)
	v_max_f32_e32 v1, v1, v1
	v_max_f32_e32 v0, v0, v1
	v_cmp_ngt_f32_e32 vcc, s55, v0
	s_nop 1
	v_cndmask_b32_e32 v4, v203, v0, vcc
	v_max_f32_e32 v1, v3, v4
	v_cmp_neq_f32_e32 vcc, s43, v1
	s_nop 1
	v_cndmask_b32_e32 v0, 0, v1, vcc
	v_sub_f32_e32 v3, v4, v0
	v_cmp_lt_f32_e32 vcc, s68, v3
	s_cbranch_vccz .LBB0_1029
	v_pk_add_f32 v[4:5], v[64:65], v[0:1] op_sel_hi:[1,0] neg_lo:[0,1] neg_hi:[0,1]
	v_pk_add_f32 v[6:7], v[72:73], v[0:1] op_sel_hi:[1,0] neg_lo:[0,1] neg_hi:[0,1]
	v_exp_f32_e32 v184, v4
	v_exp_f32_e32 v185, v5
	v_pk_add_f32 v[4:5], v[66:67], v[0:1] op_sel_hi:[1,0] neg_lo:[0,1] neg_hi:[0,1]
	v_exp_f32_e32 v72, v6
	v_exp_f32_e32 v186, v4
	v_exp_f32_e32 v187, v5
	v_pk_add_f32 v[4:5], v[68:69], v[0:1] op_sel_hi:[1,0] neg_lo:[0,1] neg_hi:[0,1]
	v_exp_f32_e32 v73, v7
	v_exp_f32_e32 v188, v4
	v_exp_f32_e32 v189, v5
	v_pk_add_f32 v[4:5], v[70:71], v[0:1] op_sel_hi:[1,0] neg_lo:[0,1] neg_hi:[0,1]
	v_pk_add_f32 v[6:7], v[74:75], v[0:1] op_sel_hi:[1,0] neg_lo:[0,1] neg_hi:[0,1]
	v_exp_f32_e32 v190, v4
	v_exp_f32_e32 v191, v5
	v_pk_add_f32 v[4:5], v[184:185], 0 op_sel_hi:[1,0]
	v_exp_f32_e32 v172, v6
	v_pk_add_f32 v[4:5], v[186:187], v[4:5]
	v_exp_f32_e32 v173, v7
	v_pk_add_f32 v[6:7], v[76:77], v[0:1] op_sel_hi:[1,0] neg_lo:[0,1] neg_hi:[0,1]
	v_pk_add_f32 v[4:5], v[188:189], v[4:5]
	v_exp_f32_e32 v174, v6
	v_exp_f32_e32 v175, v7
	v_pk_add_f32 v[6:7], v[78:79], v[0:1] op_sel_hi:[1,0] neg_lo:[0,1] neg_hi:[0,1]
	v_pk_add_f32 v[4:5], v[190:191], v[4:5]
	v_exp_f32_e32 v178, v6
	v_exp_f32_e32 v179, v7
	v_pk_add_f32 v[6:7], v[48:49], v[0:1] op_sel_hi:[1,0] neg_lo:[0,1] neg_hi:[0,1]
	v_pk_add_f32 v[4:5], v[72:73], v[4:5]
	v_exp_f32_e32 v78, v6
	v_exp_f32_e32 v79, v7
	v_pk_add_f32 v[6:7], v[50:51], v[0:1] op_sel_hi:[1,0] neg_lo:[0,1] neg_hi:[0,1]
	v_pk_add_f32 v[4:5], v[172:173], v[4:5]
	v_exp_f32_e32 v176, v6
	v_exp_f32_e32 v177, v7
	v_pk_add_f32 v[6:7], v[52:53], v[0:1] op_sel_hi:[1,0] neg_lo:[0,1] neg_hi:[0,1]
	v_pk_add_f32 v[4:5], v[174:175], v[4:5]
	v_exp_f32_e32 v180, v6
	v_exp_f32_e32 v181, v7
	v_pk_add_f32 v[6:7], v[54:55], v[0:1] op_sel_hi:[1,0] neg_lo:[0,1] neg_hi:[0,1]
	v_pk_add_f32 v[4:5], v[178:179], v[4:5]
	v_exp_f32_e32 v182, v6
	v_exp_f32_e32 v183, v7
	v_pk_add_f32 v[6:7], v[56:57], v[0:1] op_sel_hi:[1,0] neg_lo:[0,1] neg_hi:[0,1]
	v_pk_add_f32 v[4:5], v[78:79], v[4:5]
	v_exp_f32_e32 v68, v6
	v_exp_f32_e32 v69, v7
	v_pk_add_f32 v[6:7], v[58:59], v[0:1] op_sel_hi:[1,0] neg_lo:[0,1] neg_hi:[0,1]
	v_pk_add_f32 v[4:5], v[176:177], v[4:5]
	v_exp_f32_e32 v70, v6
	v_exp_f32_e32 v71, v7
	v_pk_add_f32 v[6:7], v[60:61], v[0:1] op_sel_hi:[1,0] neg_lo:[0,1] neg_hi:[0,1]
	v_pk_add_f32 v[4:5], v[180:181], v[4:5]
	v_exp_f32_e32 v74, v6
	v_exp_f32_e32 v75, v7
	v_pk_add_f32 v[6:7], v[62:63], v[0:1] op_sel_hi:[1,0] neg_lo:[0,1] neg_hi:[0,1]
	v_pk_add_f32 v[4:5], v[182:183], v[4:5]
	v_exp_f32_e32 v76, v6
	v_exp_f32_e32 v77, v7
	v_pk_add_f32 v[6:7], v[96:97], v[0:1] op_sel_hi:[1,0] neg_lo:[0,1] neg_hi:[0,1]
	v_pk_add_f32 v[4:5], v[68:69], v[4:5]
	v_exp_f32_e32 v60, v6
	v_exp_f32_e32 v61, v7
	v_pk_add_f32 v[6:7], v[98:99], v[0:1] op_sel_hi:[1,0] neg_lo:[0,1] neg_hi:[0,1]
	v_pk_add_f32 v[4:5], v[70:71], v[4:5]
	v_exp_f32_e32 v62, v6
	v_exp_f32_e32 v63, v7
	v_pk_add_f32 v[6:7], v[100:101], v[0:1] op_sel_hi:[1,0] neg_lo:[0,1] neg_hi:[0,1]
	v_pk_add_f32 v[4:5], v[74:75], v[4:5]
	v_exp_f32_e32 v64, v6
	v_exp_f32_e32 v65, v7
	v_pk_add_f32 v[6:7], v[102:103], v[0:1] op_sel_hi:[1,0] neg_lo:[0,1] neg_hi:[0,1]
	v_pk_add_f32 v[4:5], v[76:77], v[4:5]
	v_exp_f32_e32 v66, v6
	v_exp_f32_e32 v67, v7
	v_pk_add_f32 v[6:7], v[104:105], v[0:1] op_sel_hi:[1,0] neg_lo:[0,1] neg_hi:[0,1]
	v_pk_add_f32 v[4:5], v[60:61], v[4:5]
	v_exp_f32_e32 v52, v6
	v_exp_f32_e32 v53, v7
	v_pk_add_f32 v[6:7], v[106:107], v[0:1] op_sel_hi:[1,0] neg_lo:[0,1] neg_hi:[0,1]
	v_pk_add_f32 v[4:5], v[62:63], v[4:5]
	v_exp_f32_e32 v54, v6
	v_exp_f32_e32 v55, v7
	v_pk_add_f32 v[6:7], v[108:109], v[0:1] op_sel_hi:[1,0] neg_lo:[0,1] neg_hi:[0,1]
	v_pk_add_f32 v[4:5], v[64:65], v[4:5]
	v_exp_f32_e32 v56, v6
	v_exp_f32_e32 v57, v7
	v_pk_add_f32 v[6:7], v[110:111], v[0:1] op_sel_hi:[1,0] neg_lo:[0,1] neg_hi:[0,1]
	v_pk_add_f32 v[4:5], v[66:67], v[4:5]
	v_exp_f32_e32 v58, v6
	v_exp_f32_e32 v59, v7
	v_pk_add_f32 v[6:7], v[80:81], v[0:1] op_sel_hi:[1,0] neg_lo:[0,1] neg_hi:[0,1]
	v_pk_add_f32 v[4:5], v[52:53], v[4:5]
	v_exp_f32_e32 v12, v6
	v_exp_f32_e32 v13, v7
	v_pk_add_f32 v[6:7], v[82:83], v[0:1] op_sel_hi:[1,0] neg_lo:[0,1] neg_hi:[0,1]
	v_pk_add_f32 v[4:5], v[54:55], v[4:5]
	v_exp_f32_e32 v14, v6
	v_exp_f32_e32 v15, v7
	v_pk_add_f32 v[6:7], v[84:85], v[0:1] op_sel_hi:[1,0] neg_lo:[0,1] neg_hi:[0,1]
	v_pk_add_f32 v[4:5], v[56:57], v[4:5]
	v_exp_f32_e32 v48, v6
	v_exp_f32_e32 v49, v7
	v_pk_add_f32 v[6:7], v[86:87], v[0:1] op_sel_hi:[1,0] neg_lo:[0,1] neg_hi:[0,1]
	v_pk_add_f32 v[4:5], v[58:59], v[4:5]
	v_exp_f32_e32 v50, v6
	v_exp_f32_e32 v51, v7
	v_pk_add_f32 v[4:5], v[12:13], v[4:5]
	v_pk_add_f32 v[6:7], v[90:91], v[0:1] op_sel_hi:[1,0] neg_lo:[0,1] neg_hi:[0,1]
	v_pk_add_f32 v[4:5], v[14:15], v[4:5]
	v_exp_f32_e32 v6, v6
	v_pk_add_f32 v[4:5], v[48:49], v[4:5]
	v_exp_f32_e32 v7, v7
	v_pk_add_f32 v[80:81], v[50:51], v[4:5]
	v_pk_add_f32 v[4:5], v[88:89], v[0:1] op_sel_hi:[1,0] neg_lo:[0,1] neg_hi:[0,1]
	v_pk_add_f32 v[8:9], v[92:93], v[0:1] op_sel_hi:[1,0] neg_lo:[0,1] neg_hi:[0,1]
	v_exp_f32_e32 v4, v4
	v_exp_f32_e32 v5, v5
	v_exp_f32_e32 v8, v8
	v_exp_f32_e32 v9, v9
	v_pk_add_f32 v[10:11], v[94:95], v[0:1] op_sel_hi:[1,0] neg_lo:[0,1] neg_hi:[0,1]
	v_pk_add_f32 v[80:81], v[4:5], v[80:81]
	v_exp_f32_e32 v10, v10
	v_exp_f32_e32 v11, v11
	v_pk_add_f32 v[80:81], v[6:7], v[80:81]
	v_sub_f32_e32 v231, v230, v0
	v_pk_add_f32 v[80:81], v[8:9], v[80:81]
	v_exp_f32_e32 v0, v231
	v_pk_add_f32 v[80:81], v[10:11], v[80:81]
	v_cmp_gt_f32_e32 vcc, v1, v230
	v_add_f32_e32 v3, v80, v81
	ds_bpermute_b32 v80, v215, v3
	s_cbranch_vccz .LBB0_1026
; template <int BR, int NT, int DV> ...
;     ...
;             if (__builtin_amdgcn_ballot_w64(grow) != 0ull) {
; #pragma unroll
;                 for (int i = 0; i < 16; ++i) { O[0][i] *= alpha; O[1][i] *= alpha; }
;             }
	v_pk_mul_f32 v[46:47], v[46:47], v[0:1] op_sel_hi:[1,0]
	v_pk_mul_f32 v[44:45], v[44:45], v[0:1] op_sel_hi:[1,0]
	v_pk_mul_f32 v[42:43], v[42:43], v[0:1] op_sel_hi:[1,0]
	v_pk_mul_f32 v[40:41], v[40:41], v[0:1] op_sel_hi:[1,0]
	v_pk_mul_f32 v[38:39], v[38:39], v[0:1] op_sel_hi:[1,0]
	v_pk_mul_f32 v[36:37], v[36:37], v[0:1] op_sel_hi:[1,0]
	v_pk_mul_f32 v[34:35], v[34:35], v[0:1] op_sel_hi:[1,0]
	v_pk_mul_f32 v[32:33], v[32:33], v[0:1] op_sel_hi:[1,0]
	v_pk_mul_f32 v[30:31], v[30:31], v[0:1] op_sel_hi:[1,0]
	v_pk_mul_f32 v[28:29], v[28:29], v[0:1] op_sel_hi:[1,0]
	v_pk_mul_f32 v[26:27], v[26:27], v[0:1] op_sel_hi:[1,0]
	v_pk_mul_f32 v[24:25], v[24:25], v[0:1] op_sel_hi:[1,0]
	v_pk_mul_f32 v[22:23], v[22:23], v[0:1] op_sel_hi:[1,0]
	v_pk_mul_f32 v[20:21], v[20:21], v[0:1] op_sel_hi:[1,0]
	v_pk_mul_f32 v[18:19], v[18:19], v[0:1] op_sel_hi:[1,0]
	v_pk_mul_f32 v[16:17], v[16:17], v[0:1] op_sel_hi:[1,0]

; #define LAS __attribute__((address_space(3)))
; DI unsigned f2bf(float f) { return pk2(f, 0.f) & 0xffffu; }
; #define MFMA32(a, b, c) __builtin_amdgcn_mfma_f32_32x32x16_bf16((a), (b), (c), 0, 0, 0)
; template <int BR, int NT, int DV> ...
;     ...
;     for (int ti = 0; ti < NT; ++ti) {
;         LAS unsigned char* kb = ti ? kbB : kbA; const int j = ti ? jB : jA;
; #pragma unroll
;         for (int i = 0; i < 16; ++i) { s[2 * ti][i] = 0.f; s[2 * ti + 1][i] = 0.f; }
; #pragma unroll
;         for (int ks = 0; ks < ((DV & 4) ? 0 : 4); ++ks) {
;             const bf16x8 a0 = *(const LAS bf16x8*)(kb + c.n * 144 + ks * 32 + c.h * 16);
;             const bf16x8 a1 = *(const LAS bf16x8*)(kb + (32 + c.n) * 144 + ks * 32 + c.h * 16);
;             s[2 * ti] = MFMA32(a0, c.qf[ks], s[2 * ti]); s[2 * ti + 1] = MFMA32(a1, c.qf[ks], s[2 * ti + 1]);
;         }
;         {
;             const int pos0 = (BR <= 1) ? (1024 * j + 31 - c.t) : (64 * j - c.t);
;             float tb = c.slope2 * (float)pos0;
;             if (BR == 2) { if (!m128_bit(c.sel_lo, c.sel_hi, j)) tb = -1e30f; }
;             const unsigned thi = f2bf(tb); const unsigned tlo = f2bf(tb - bf2f(thi));
;             u32x4 bw = (u32x4){(BR <= 1) ? c.slope16w : c.slopew, thi | (tlo << 16), 0u, 0u};
;             if (c.h) bw = (u32x4){0u, 0u, 0u, 0u};
;             const bf16x8 bb = __builtin_bit_cast(bf16x8, bw);
;             s[2 * ti] = MFMA32(c.akey[0], bb, s[2 * ti]); s[2 * ti + 1] = MFMA32(c.akey[1], bb, s[2 * ti + 1]);
;         }
;     ...
;     float mx = -INFINITY;
; #pragma unroll
;     for (int q = 0; q < 2 * NT; ++q)
; #pragma unroll
;         for (int i = 0; i < 16; ++i) mx = fmaxf(mx, s[q][i]);
.LBB0_1085:
	ds_read_b128 v[22:25], v20 offset:13888
	ds_read_b128 v[26:29], v20 offset:9312
	ds_read_b128 v[166:169], v20 offset:13920
	s_lshl_b32 s13, s16, 6
	v_sub_u32_e32 v1, s13, v209
	s_waitcnt lgkmcnt(7)
	v_mfma_f32_32x32x16_bf16 v[80:95], v[232:235], v[112:115], 0
	v_cvt_f32_i32_e32 v1, v1
	s_cmp_eq_u32 s16, s93
	s_cselect_b64 s[20:21], -1, 0
	s_add_i32 s16, s16, 8
	v_mul_f32_e32 v3, v210, v1
	v_cvt_pk_bf16_f32 v3, v3, 0
	s_waitcnt lgkmcnt(6)
	v_mfma_f32_32x32x16_bf16 v[96:111], v[236:239], v[112:115], 0
	v_max3_f32 v252, v64, s43, v65
	v_max3_f32 v252, v252, v66, v67
	s_cmp_eq_u32 s16, s93
	s_cselect_b64 s[22:23], -1, 0
	s_or_b64 s[20:21], s[20:21], s[22:23]
	s_andn2_b64 vcc, exec, s[20:21]
	s_waitcnt lgkmcnt(5)
	v_mfma_f32_32x32x16_bf16 v[96:111], v[240:243], v[116:119], v[96:111]
	v_max3_f32 v252, v252, v68, v69
	v_max3_f32 v252, v252, v70, v71
	s_waitcnt lgkmcnt(4)
	v_mfma_f32_32x32x16_bf16 v[80:95], v[244:247], v[116:119], v[80:95]
	v_max3_f32 v252, v252, v72, v73
	v_max3_f32 v252, v252, v74, v75
	s_waitcnt lgkmcnt(3)
	v_mfma_f32_32x32x16_bf16 v[96:111], v[248:251], v[120:123], v[96:111]
	v_max3_f32 v252, v252, v76, v77
	v_max3_f32 v252, v252, v78, v79
	s_waitcnt lgkmcnt(2)
	v_mfma_f32_32x32x16_bf16 v[80:95], v[22:25], v[120:123], v[80:95]
	v_max3_f32 v252, v252, v4, v5
	v_max3_f32 v252, v252, v6, v7
	v_and_b32_e32 v20, 0xffff, v3
	v_lshlrev_b32_e32 v3, 16, v3
	v_fma_f32 v1, v210, v1, -v3
	v_cvt_pk_bf16_f32 v1, v1, 0
	v_lshl_or_b32 v1, v1, 16, v20
	v_cndmask_b32_e64 v1, 0, v1, s[6:7]
	s_waitcnt lgkmcnt(1)
	v_mfma_f32_32x32x16_bf16 v[96:111], v[26:29], v[124:127], v[96:111]
	v_max3_f32 v252, v252, v8, v9
	v_max3_f32 v252, v252, v10, v11
	v_mov_b32_e32 v3, v2
	s_waitcnt lgkmcnt(0)
	v_mfma_f32_32x32x16_bf16 v[80:95], v[166:169], v[124:127], v[80:95]
	v_max3_f32 v252, v252, v12, v13
	v_max3_f32 v252, v252, v14, v15
	v_mfma_f32_32x32x16_bf16 v[96:111], v[128:131], v[0:3], v[96:111]
	v_max3_f32 v252, v252, v16, v17
	v_max3_f32 v252, v252, v18, v19
	v_mfma_f32_32x32x16_bf16 v[80:95], v[132:135], v[0:3], v[80:95]
	s_cbranch_vccnz .LBB0_1087
	v_or_b32_e32 v0, s13, v154
	v_sub_u32_e32 v1, v209, v0
	v_cmp_gt_u32_e32 vcc, s41, v1
	v_sub_u32_e32 v1, v0, v209
	s_nop 5
	v_cndmask_b32_e32 v96, v203, v96, vcc
	v_cmp_lt_u32_e32 vcc, s96, v1
	v_sub_u32_e32 v1, v187, v0
	s_nop 0
	v_cndmask_b32_e32 v97, v203, v97, vcc
	v_cmp_gt_u32_e32 vcc, s41, v1
	v_sub_u32_e32 v1, v188, v0
	s_nop 0
	v_cndmask_b32_e32 v98, v203, v98, vcc
	v_cmp_gt_u32_e32 vcc, s41, v1
	v_or_b32_e32 v1, s13, v189
	v_sub_u32_e32 v3, v209, v1
	v_cndmask_b32_e32 v99, v203, v99, vcc
	v_cmp_gt_u32_e32 vcc, s41, v3
	v_sub_u32_e32 v3, v1, v209
	s_nop 0
	v_cndmask_b32_e32 v100, v203, v100, vcc
	v_cmp_lt_u32_e32 vcc, s96, v3
	v_sub_u32_e32 v3, v187, v1
	s_nop 0
	v_cndmask_b32_e32 v101, v203, v101, vcc
	v_cmp_gt_u32_e32 vcc, s41, v3
	v_sub_u32_e32 v3, v188, v1
	s_nop 0
	v_cndmask_b32_e32 v102, v203, v102, vcc
	v_cmp_gt_u32_e32 vcc, s41, v3
	v_or_b32_e32 v3, s13, v190
	v_sub_u32_e32 v20, v209, v3
	v_cndmask_b32_e32 v103, v203, v103, vcc
	v_cmp_gt_u32_e32 vcc, s41, v20
	v_sub_u32_e32 v20, v3, v209
	s_nop 0
	v_cndmask_b32_e32 v104, v203, v104, vcc
	v_cmp_lt_u32_e32 vcc, s96, v20
	v_sub_u32_e32 v20, v187, v3
	s_nop 0
	v_cndmask_b32_e32 v105, v203, v105, vcc
	v_cmp_gt_u32_e32 vcc, s41, v20
	v_sub_u32_e32 v20, v188, v3
	s_nop 0
	v_cndmask_b32_e32 v106, v203, v106, vcc
	v_cmp_gt_u32_e32 vcc, s41, v20
	v_or_b32_e32 v20, s13, v191
	v_sub_u32_e32 v21, v209, v20
	v_cndmask_b32_e32 v107, v203, v107, vcc
	v_cmp_gt_u32_e32 vcc, s41, v21
	v_sub_u32_e32 v21, v20, v209
	s_nop 0
	v_cndmask_b32_e32 v108, v203, v108, vcc
	v_cmp_lt_u32_e32 vcc, s96, v21
	v_sub_u32_e32 v21, v187, v20
	s_nop 0
	v_cndmask_b32_e32 v109, v203, v109, vcc
	v_cmp_gt_u32_e32 vcc, s41, v21
	v_sub_u32_e32 v21, v188, v20
	s_nop 0
	v_cndmask_b32_e32 v110, v203, v110, vcc
	v_cmp_gt_u32_e32 vcc, s41, v21
	v_sub_u32_e32 v21, v214, v0
	s_nop 0
	v_cndmask_b32_e32 v111, v203, v111, vcc
	v_cmp_gt_u32_e32 vcc, s41, v21
	v_sub_u32_e32 v21, v216, v0
	s_nop 0
	v_cndmask_b32_e32 v80, v203, v80, vcc
	v_cmp_gt_u32_e32 vcc, s41, v21
	v_sub_u32_e32 v21, v217, v0
	v_sub_u32_e32 v0, v218, v0
	v_cndmask_b32_e32 v81, v203, v81, vcc
	v_cmp_gt_u32_e32 vcc, s41, v21
	s_nop 1
	v_cndmask_b32_e32 v82, v203, v82, vcc
	v_cmp_gt_u32_e32 vcc, s41, v0
	v_sub_u32_e32 v0, v214, v1
	s_nop 0
	v_cndmask_b32_e32 v83, v203, v83, vcc
	v_cmp_gt_u32_e32 vcc, s41, v0
	v_sub_u32_e32 v0, v216, v1
	s_nop 0
	v_cndmask_b32_e32 v84, v203, v84, vcc
	v_cmp_gt_u32_e32 vcc, s41, v0
	v_sub_u32_e32 v0, v217, v1
	s_nop 0
	v_cndmask_b32_e32 v85, v203, v85, vcc
	v_cmp_gt_u32_e32 vcc, s41, v0
	v_sub_u32_e32 v0, v218, v1
	s_nop 0
	v_cndmask_b32_e32 v86, v203, v86, vcc
	v_cmp_gt_u32_e32 vcc, s41, v0
	v_sub_u32_e32 v0, v214, v3
	s_nop 0
	v_cndmask_b32_e32 v87, v203, v87, vcc
	v_cmp_gt_u32_e32 vcc, s41, v0
	v_sub_u32_e32 v0, v216, v3
	s_nop 0
	v_cndmask_b32_e32 v88, v203, v88, vcc
	v_cmp_gt_u32_e32 vcc, s41, v0
	v_sub_u32_e32 v0, v217, v3
	s_nop 0
	v_cndmask_b32_e32 v89, v203, v89, vcc
	v_cmp_gt_u32_e32 vcc, s41, v0
	v_sub_u32_e32 v0, v218, v3
	s_nop 0
	v_cndmask_b32_e32 v90, v203, v90, vcc
	v_cmp_gt_u32_e32 vcc, s41, v0
	v_sub_u32_e32 v0, v214, v20
	s_nop 0
	v_cndmask_b32_e32 v91, v203, v91, vcc
	v_cmp_gt_u32_e32 vcc, s41, v0
	v_sub_u32_e32 v0, v216, v20
	s_nop 0
	v_cndmask_b32_e32 v92, v203, v92, vcc
	v_cmp_gt_u32_e32 vcc, s41, v0
	v_sub_u32_e32 v0, v217, v20
	s_nop 0
	v_cndmask_b32_e32 v93, v203, v93, vcc
	v_cmp_gt_u32_e32 vcc, s41, v0
	v_sub_u32_e32 v0, v218, v20
	s_nop 0
	v_cndmask_b32_e32 v94, v203, v94, vcc
	v_cmp_gt_u32_e32 vcc, s41, v0
	s_nop 1
	v_cndmask_b32_e32 v95, v203, v95, vcc
; template <int BR, int NT, int DV> ...
;     ...
;     float mx = -INFINITY;
; #pragma unroll
;     for (int q = 0; q < 2 * NT; ++q)
; #pragma unroll
;         for (int i = 0; i < 16; ++i) mx = fmaxf(mx, s[q][i]);
;     if (BR == 1) { m_use = m_fin; }
;     else {
;         mx = fmaxf(mx, __shfl_xor(mx, 32));
;         if (mx < -1e29f) mx = -INFINITY;
;         const float m_new = fmaxf(m, mx);
;         grow = m_new > m;
;         m_use = (m_new == -INFINITY) ? 0.f : m_new;
;         alpha = __builtin_amdgcn_exp2f(m - m_use);
;         m = m_new;
;     }
;     if (__builtin_amdgcn_ballot_w64((mx - m_use) > -150.f) == 0ull) {
;         if (BR == 1) {
; #pragma unroll
;             for (int ti = 0; ti < NT; ++ti)
; #pragma unroll
;                 for (int kt = 0; kt < 2; ++kt)
; #pragma unroll
;                     for (int v = 0; v < 4; ++v) { const int j = ti ? jB : jA; const float add = c.h ? 0.f : carry; carry = 0.f; if (c.r == 0) imp_row[16 * j + 8 * kt + 2 * v + c.h] = add; }
;         }
;         return;
;     }
;     f32x2_t sum2 = {0.f, 0.f}; const f32x2_t mm2 = {m_use, m_use}, il2 = {inv_l, inv_l};
; #pragma unroll
;     for (int q = 0; q < 2 * NT; ++q)
; #pragma unroll
;         for (int rr = 0; rr < 16; rr += 2) {
;             const f32x2_t d = (f32x2_t){s[q][rr], s[q][rr + 1]} - mm2;
;             f32x2_t p = (DV & 1) ? d : (f32x2_t){__builtin_amdgcn_exp2f(d.x), __builtin_amdgcn_exp2f(d.y)};
;             if (BR == 1) p *= il2;
;             s[q][rr] = p.x; s[q][rr + 1] = p.y; sum2 += p;
;         }
;     float sum = sum2.x + sum2.y;
;     if (BR != 1) { sum += __shfl_xor(sum, 32); l = l * alpha + sum; }
.LBB0_1087:
	v_max3_f32 v0, v252, v96, v97
	v_max3_f32 v0, v0, v98, v99
	v_max3_f32 v0, v0, v100, v101
	v_max3_f32 v0, v0, v102, v103
	v_max3_f32 v0, v0, v104, v105
	v_max3_f32 v0, v0, v106, v107
	v_max3_f32 v0, v0, v108, v109
	v_max3_f32 v0, v0, v110, v111
	v_max3_f32 v0, v0, v80, v81
	v_max3_f32 v0, v0, v82, v83
	v_max3_f32 v0, v0, v84, v85
	v_max3_f32 v0, v0, v86, v87
	v_max3_f32 v0, v0, v88, v89
	v_max3_f32 v0, v0, v90, v91
	v_max3_f32 v0, v0, v92, v93
	v_max3_f32 v0, v0, v94, v95
	ds_bpermute_b32 v1, v215, v0
	v_max_f32_e32 v3, v220, v220
	s_waitcnt lgkmcnt(0)
	v_max_f32_e32 v1, v1, v1
	v_max_f32_e32 v0, v0, v1
	v_cmp_ngt_f32_e32 vcc, s55, v0
	s_nop 1
	v_cndmask_b32_e32 v20, v203, v0, vcc
	v_max_f32_e32 v1, v3, v20
	v_cmp_neq_f32_e32 vcc, s43, v1
	s_nop 1
	v_cndmask_b32_e32 v0, 0, v1, vcc
	v_sub_f32_e32 v3, v20, v0
	v_cmp_lt_f32_e32 vcc, s68, v3
	s_cbranch_vccz .LBB0_1093
	v_pk_add_f32 v[20:21], v[64:65], v[0:1] op_sel_hi:[1,0] neg_lo:[0,1] neg_hi:[0,1]
	v_pk_add_f32 v[22:23], v[72:73], v[0:1] op_sel_hi:[1,0] neg_lo:[0,1] neg_hi:[0,1]
	v_exp_f32_e32 v178, v20
	v_exp_f32_e32 v179, v21
	v_pk_add_f32 v[20:21], v[66:67], v[0:1] op_sel_hi:[1,0] neg_lo:[0,1] neg_hi:[0,1]
	v_exp_f32_e32 v72, v22
	v_exp_f32_e32 v180, v20
	v_exp_f32_e32 v181, v21
	v_pk_add_f32 v[20:21], v[68:69], v[0:1] op_sel_hi:[1,0] neg_lo:[0,1] neg_hi:[0,1]
	v_exp_f32_e32 v73, v23
	v_exp_f32_e32 v182, v20
	v_exp_f32_e32 v183, v21
	v_pk_add_f32 v[20:21], v[70:71], v[0:1] op_sel_hi:[1,0] neg_lo:[0,1] neg_hi:[0,1]
	v_pk_add_f32 v[22:23], v[74:75], v[0:1] op_sel_hi:[1,0] neg_lo:[0,1] neg_hi:[0,1]
	v_exp_f32_e32 v184, v20
	v_exp_f32_e32 v185, v21
	v_pk_add_f32 v[20:21], v[178:179], 0 op_sel_hi:[1,0]
	v_exp_f32_e32 v166, v22
	v_pk_add_f32 v[20:21], v[180:181], v[20:21]
	v_exp_f32_e32 v167, v23
	v_pk_add_f32 v[22:23], v[76:77], v[0:1] op_sel_hi:[1,0] neg_lo:[0,1] neg_hi:[0,1]
	v_pk_add_f32 v[20:21], v[182:183], v[20:21]
	v_exp_f32_e32 v168, v22
	v_exp_f32_e32 v169, v23
	v_pk_add_f32 v[22:23], v[78:79], v[0:1] op_sel_hi:[1,0] neg_lo:[0,1] neg_hi:[0,1]
	v_pk_add_f32 v[20:21], v[184:185], v[20:21]
	v_exp_f32_e32 v172, v22
	v_exp_f32_e32 v173, v23
	v_pk_add_f32 v[4:5], v[4:5], v[0:1] op_sel_hi:[1,0] neg_lo:[0,1] neg_hi:[0,1]
	v_pk_add_f32 v[20:21], v[72:73], v[20:21]
	v_exp_f32_e32 v78, v4
	v_exp_f32_e32 v79, v5
	v_pk_add_f32 v[4:5], v[6:7], v[0:1] op_sel_hi:[1,0] neg_lo:[0,1] neg_hi:[0,1]
	v_pk_add_f32 v[20:21], v[166:167], v[20:21]
	v_exp_f32_e32 v170, v4
	v_exp_f32_e32 v171, v5
	v_pk_add_f32 v[4:5], v[8:9], v[0:1] op_sel_hi:[1,0] neg_lo:[0,1] neg_hi:[0,1]
	v_pk_add_f32 v[20:21], v[168:169], v[20:21]
	v_exp_f32_e32 v174, v4
	v_exp_f32_e32 v175, v5
	v_pk_add_f32 v[4:5], v[10:11], v[0:1] op_sel_hi:[1,0] neg_lo:[0,1] neg_hi:[0,1]
	v_pk_add_f32 v[20:21], v[172:173], v[20:21]
	v_exp_f32_e32 v176, v4
	v_exp_f32_e32 v177, v5
	v_pk_add_f32 v[6:7], v[12:13], v[0:1] op_sel_hi:[1,0] neg_lo:[0,1] neg_hi:[0,1]
	v_pk_add_f32 v[4:5], v[78:79], v[20:21]
	v_exp_f32_e32 v68, v6
	v_exp_f32_e32 v69, v7
	v_pk_add_f32 v[6:7], v[14:15], v[0:1] op_sel_hi:[1,0] neg_lo:[0,1] neg_hi:[0,1]
	v_pk_add_f32 v[4:5], v[170:171], v[4:5]
	v_exp_f32_e32 v70, v6
	v_exp_f32_e32 v71, v7
	v_pk_add_f32 v[6:7], v[16:17], v[0:1] op_sel_hi:[1,0] neg_lo:[0,1] neg_hi:[0,1]
	v_pk_add_f32 v[4:5], v[174:175], v[4:5]
	v_exp_f32_e32 v74, v6
	v_exp_f32_e32 v75, v7
	v_pk_add_f32 v[6:7], v[18:19], v[0:1] op_sel_hi:[1,0] neg_lo:[0,1] neg_hi:[0,1]
	v_pk_add_f32 v[4:5], v[176:177], v[4:5]
	v_exp_f32_e32 v76, v6
	v_exp_f32_e32 v77, v7
	v_pk_add_f32 v[6:7], v[96:97], v[0:1] op_sel_hi:[1,0] neg_lo:[0,1] neg_hi:[0,1]
	v_pk_add_f32 v[4:5], v[68:69], v[4:5]
	v_exp_f32_e32 v28, v6
	v_exp_f32_e32 v29, v7
	v_pk_add_f32 v[6:7], v[98:99], v[0:1] op_sel_hi:[1,0] neg_lo:[0,1] neg_hi:[0,1]
	v_pk_add_f32 v[4:5], v[70:71], v[4:5]
	v_exp_f32_e32 v30, v6
	v_exp_f32_e32 v31, v7
	v_pk_add_f32 v[6:7], v[100:101], v[0:1] op_sel_hi:[1,0] neg_lo:[0,1] neg_hi:[0,1]
	v_pk_add_f32 v[4:5], v[74:75], v[4:5]
	v_exp_f32_e32 v64, v6
	v_exp_f32_e32 v65, v7
	v_pk_add_f32 v[6:7], v[102:103], v[0:1] op_sel_hi:[1,0] neg_lo:[0,1] neg_hi:[0,1]
	v_pk_add_f32 v[4:5], v[76:77], v[4:5]
	v_exp_f32_e32 v66, v6
	v_exp_f32_e32 v67, v7
	v_pk_add_f32 v[6:7], v[104:105], v[0:1] op_sel_hi:[1,0] neg_lo:[0,1] neg_hi:[0,1]
	v_pk_add_f32 v[4:5], v[28:29], v[4:5]
	v_exp_f32_e32 v20, v6
	v_exp_f32_e32 v21, v7
	v_pk_add_f32 v[6:7], v[106:107], v[0:1] op_sel_hi:[1,0] neg_lo:[0,1] neg_hi:[0,1]
	v_pk_add_f32 v[4:5], v[30:31], v[4:5]
	v_exp_f32_e32 v22, v6
	v_exp_f32_e32 v23, v7
	v_pk_add_f32 v[6:7], v[108:109], v[0:1] op_sel_hi:[1,0] neg_lo:[0,1] neg_hi:[0,1]
	v_pk_add_f32 v[4:5], v[64:65], v[4:5]
	v_exp_f32_e32 v24, v6
	v_exp_f32_e32 v25, v7
	v_pk_add_f32 v[6:7], v[110:111], v[0:1] op_sel_hi:[1,0] neg_lo:[0,1] neg_hi:[0,1]
	v_pk_add_f32 v[4:5], v[66:67], v[4:5]
	v_exp_f32_e32 v26, v6
	v_exp_f32_e32 v27, v7
	v_pk_add_f32 v[6:7], v[80:81], v[0:1] op_sel_hi:[1,0] neg_lo:[0,1] neg_hi:[0,1]
	v_pk_add_f32 v[4:5], v[20:21], v[4:5]
	v_exp_f32_e32 v12, v6
	v_exp_f32_e32 v13, v7
	v_pk_add_f32 v[6:7], v[82:83], v[0:1] op_sel_hi:[1,0] neg_lo:[0,1] neg_hi:[0,1]
	v_pk_add_f32 v[4:5], v[22:23], v[4:5]
	v_exp_f32_e32 v14, v6
	v_exp_f32_e32 v15, v7
	v_pk_add_f32 v[6:7], v[84:85], v[0:1] op_sel_hi:[1,0] neg_lo:[0,1] neg_hi:[0,1]
	v_pk_add_f32 v[4:5], v[24:25], v[4:5]
	v_exp_f32_e32 v16, v6
	v_exp_f32_e32 v17, v7
	v_pk_add_f32 v[6:7], v[86:87], v[0:1] op_sel_hi:[1,0] neg_lo:[0,1] neg_hi:[0,1]
	v_pk_add_f32 v[4:5], v[26:27], v[4:5]
	v_exp_f32_e32 v18, v6
	v_exp_f32_e32 v19, v7
	v_pk_add_f32 v[4:5], v[12:13], v[4:5]
	v_pk_add_f32 v[6:7], v[90:91], v[0:1] op_sel_hi:[1,0] neg_lo:[0,1] neg_hi:[0,1]
	v_pk_add_f32 v[4:5], v[14:15], v[4:5]
	v_exp_f32_e32 v6, v6
	v_pk_add_f32 v[4:5], v[16:17], v[4:5]
	v_exp_f32_e32 v7, v7
	v_pk_add_f32 v[80:81], v[18:19], v[4:5]
	v_pk_add_f32 v[4:5], v[88:89], v[0:1] op_sel_hi:[1,0] neg_lo:[0,1] neg_hi:[0,1]
	v_pk_add_f32 v[8:9], v[92:93], v[0:1] op_sel_hi:[1,0] neg_lo:[0,1] neg_hi:[0,1]
	v_exp_f32_e32 v4, v4
	v_exp_f32_e32 v5, v5
	v_exp_f32_e32 v8, v8
	v_exp_f32_e32 v9, v9
	v_pk_add_f32 v[10:11], v[94:95], v[0:1] op_sel_hi:[1,0] neg_lo:[0,1] neg_hi:[0,1]
	v_pk_add_f32 v[80:81], v[4:5], v[80:81]
	v_exp_f32_e32 v10, v10
	v_exp_f32_e32 v11, v11
	v_pk_add_f32 v[80:81], v[6:7], v[80:81]
	v_sub_f32_e32 v221, v220, v0
	v_pk_add_f32 v[80:81], v[8:9], v[80:81]
	v_exp_f32_e32 v0, v221
	v_pk_add_f32 v[80:81], v[10:11], v[80:81]
	v_cmp_gt_f32_e32 vcc, v1, v220
	v_add_f32_e32 v3, v80, v81
	ds_bpermute_b32 v80, v215, v3
	s_cbranch_vccz .LBB0_1090
; template <int BR, int NT, int DV> ...
;     ...
;             if (__builtin_amdgcn_ballot_w64(grow) != 0ull) {
; #pragma unroll
;                 for (int i = 0; i < 16; ++i) { O[0][i] *= alpha; O[1][i] *= alpha; }
;             }
	v_pk_mul_f32 v[62:63], v[62:63], v[0:1] op_sel_hi:[1,0]
	v_pk_mul_f32 v[60:61], v[60:61], v[0:1] op_sel_hi:[1,0]
	v_pk_mul_f32 v[58:59], v[58:59], v[0:1] op_sel_hi:[1,0]
	v_pk_mul_f32 v[56:57], v[56:57], v[0:1] op_sel_hi:[1,0]
	v_pk_mul_f32 v[54:55], v[54:55], v[0:1] op_sel_hi:[1,0]
	v_pk_mul_f32 v[52:53], v[52:53], v[0:1] op_sel_hi:[1,0]
	v_pk_mul_f32 v[50:51], v[50:51], v[0:1] op_sel_hi:[1,0]
	v_pk_mul_f32 v[48:49], v[48:49], v[0:1] op_sel_hi:[1,0]
	v_pk_mul_f32 v[46:47], v[46:47], v[0:1] op_sel_hi:[1,0]
	v_pk_mul_f32 v[44:45], v[44:45], v[0:1] op_sel_hi:[1,0]
	v_pk_mul_f32 v[42:43], v[42:43], v[0:1] op_sel_hi:[1,0]
	v_pk_mul_f32 v[40:41], v[40:41], v[0:1] op_sel_hi:[1,0]
	v_pk_mul_f32 v[38:39], v[38:39], v[0:1] op_sel_hi:[1,0]
	v_pk_mul_f32 v[36:37], v[36:37], v[0:1] op_sel_hi:[1,0]
	v_pk_mul_f32 v[34:35], v[34:35], v[0:1] op_sel_hi:[1,0]
	v_pk_mul_f32 v[32:33], v[32:33], v[0:1] op_sel_hi:[1,0]
